# attention top-k list compaction made branch-free (instruction selection in a VALU/branch-bound section): v_cmp + saveexec + ds_write per slot, no per-slot exec branches
# baseline (speedup 1.0000x reference)
.LBB0_2504:
	v_readlane_b32 s52, v251, 35
	v_readlane_b32 s53, v251, 36
	v_readlane_b32 s54, v251, 37
	v_readlane_b32 s55, v251, 38
	v_readlane_b32 s64, v251, 47
	v_readlane_b32 s65, v251, 48
	v_readlane_b32 s56, v251, 39
	v_readlane_b32 s57, v251, 40
	v_readlane_b32 s58, v251, 41
	v_readlane_b32 s59, v251, 42
	v_readlane_b32 s60, v251, 43
	v_readlane_b32 s61, v251, 44
	v_readlane_b32 s62, v251, 45
	v_readlane_b32 s63, v251, 46
	v_readlane_b32 s66, v251, 49
	v_readlane_b32 s67, v251, 50
	s_mov_b64 s[52:53], s[64:65]
	s_mov_b64 s[54:55], s[66:67]
	v_readlane_b32 s56, v251, 19
	v_readlane_b32 s57, v251, 20
	v_readlane_b32 s58, v251, 21
	v_readlane_b32 s59, v251, 22
	v_readlane_b32 s60, v251, 23
	v_readlane_b32 s61, v251, 24
	v_readlane_b32 s62, v251, 25
	v_readlane_b32 s63, v251, 26
	v_readlane_b32 s64, v251, 27
	v_readlane_b32 s65, v251, 28
	v_readlane_b32 s4, v252, 7
	v_readlane_b32 s66, v251, 29
	v_readlane_b32 s67, v251, 30
	v_readlane_b32 s68, v251, 31
	v_readlane_b32 s69, v251, 32
	v_readlane_b32 s70, v251, 33
	v_readlane_b32 s71, v251, 34
	s_mov_b64 s[56:57], s[64:65]
	s_and_b64 vcc, exec, s[16:17]
	v_readlane_b32 s5, v252, 8
	v_readlane_b32 s6, v252, 9
	v_readlane_b32 s7, v252, 10
	s_mov_b64 s[58:59], s[66:67]
	s_mov_b64 s[60:61], s[68:69]
	v_readlane_b32 s20, v252, 26
	v_readlane_b32 s21, v252, 24
	s_mov_b64 s[62:63], s[70:71]
	s_cbranch_vccz .LBB0_2554
	v_add_u32_e32 v10, -1, v182
	v_cmp_lt_i32_e32 vcc, v10, v40
	v_add_u32_e32 v9, v41, v42
	v_add_u32_e32 v41, -2, v182
	v_cndmask_b32_e32 v10, v10, v182, vcc
	v_lshlrev_b32_e32 v10, 2, v10
	ds_bpermute_b32 v10, v10, v9
	v_cmp_ne_u32_e32 vcc, 0, v11
	s_waitcnt lgkmcnt(0)
	s_nop 0
	v_cndmask_b32_e32 v10, 0, v10, vcc
	v_cmp_lt_i32_e32 vcc, v41, v40
	v_add_u32_e32 v10, v10, v9
	s_nop 0
	v_cndmask_b32_e32 v41, v41, v182, vcc
	v_lshlrev_b32_e32 v41, 2, v41
	ds_bpermute_b32 v41, v41, v10
	v_cmp_lt_u32_e32 vcc, 1, v11
	s_waitcnt lgkmcnt(0)
	s_nop 0
	v_cndmask_b32_e32 v41, 0, v41, vcc
	v_add_u32_e32 v10, v41, v10
	v_add_u32_e32 v41, -4, v182
	v_cmp_lt_i32_e32 vcc, v41, v40
	s_nop 1
	v_cndmask_b32_e32 v41, v41, v182, vcc
	v_lshlrev_b32_e32 v41, 2, v41
	ds_bpermute_b32 v41, v41, v10
	v_cmp_lt_u32_e32 vcc, 3, v11
	s_waitcnt lgkmcnt(0)
	s_nop 0
	v_cndmask_b32_e32 v41, 0, v41, vcc
	v_add_u32_e32 v10, v41, v10
	v_add_u32_e32 v41, -8, v182
	v_cmp_lt_i32_e32 vcc, v41, v40
	s_nop 1
	v_cndmask_b32_e32 v41, v41, v182, vcc
	v_lshlrev_b32_e32 v41, 2, v41
	ds_bpermute_b32 v41, v41, v10
	v_cmp_lt_u32_e32 vcc, 7, v11
	s_waitcnt lgkmcnt(0)
	s_nop 0
	v_cndmask_b32_e32 v41, 0, v41, vcc
	v_add_u32_e32 v10, v41, v10
	v_add_u32_e32 v41, -16, v182
	v_cmp_lt_i32_e32 vcc, v41, v40
	s_nop 1
	v_cndmask_b32_e32 v41, v41, v182, vcc
	v_lshlrev_b32_e32 v41, 2, v41
	ds_bpermute_b32 v41, v41, v10
	v_cmp_lt_u32_e32 vcc, 15, v11
	s_waitcnt lgkmcnt(0)
	s_nop 0
	v_cndmask_b32_e32 v41, 0, v41, vcc
	v_add_u32_e32 v10, v41, v10
	v_subrev_u32_e32 v41, 32, v182
	v_cmp_lt_i32_e32 vcc, v41, v40
	v_sub_u32_e32 v9, v10, v9
	s_nop 0
	v_cndmask_b32_e32 v40, v41, v182, vcc
	v_lshlrev_b32_e32 v40, 2, v40
	ds_bpermute_b32 v40, v40, v10
	v_cmp_lt_u32_e32 vcc, 31, v11
	s_waitcnt lgkmcnt(0)
	s_nop 0
	v_cndmask_b32_e32 v40, 0, v40, vcc
	v_add_u32_e32 v9, v9, v40
	v_lshl_add_u32 v40, v9, 2, v138
	v_cmp_le_u32_e32 vcc, s22, v8
	s_and_saveexec_b64 s[0:1], vcc
	ds_write_b32 v40, v11
	v_add_u32_e32 v40, 4, v40
	s_or_b64 exec, exec, s[0:1]
	v_cmp_le_u32_e32 vcc, s22, v1
	s_and_saveexec_b64 s[0:1], vcc
	v_or_b32_e32 v41, 0x40, v11
	ds_write_b32 v40, v41
	v_add_u32_e32 v40, 4, v40
	s_or_b64 exec, exec, s[0:1]
	v_cmp_le_u32_e32 vcc, s22, v2
	s_and_saveexec_b64 s[0:1], vcc
	v_or_b32_e32 v41, 0x80, v11
	ds_write_b32 v40, v41
	v_add_u32_e32 v40, 4, v40
	s_or_b64 exec, exec, s[0:1]
	v_cmp_le_u32_e32 vcc, s22, v3
	s_and_saveexec_b64 s[0:1], vcc
	v_or_b32_e32 v41, 0xc0, v11
	ds_write_b32 v40, v41
	v_add_u32_e32 v40, 4, v40
	s_or_b64 exec, exec, s[0:1]
	v_cmp_le_u32_e32 vcc, s22, v4
	s_and_saveexec_b64 s[0:1], vcc
	v_or_b32_e32 v41, 0x100, v11
	ds_write_b32 v40, v41
	v_add_u32_e32 v40, 4, v40
	s_or_b64 exec, exec, s[0:1]
	v_cmp_le_u32_e32 vcc, s22, v5
	s_and_saveexec_b64 s[0:1], vcc
	v_or_b32_e32 v41, 0x140, v11
	ds_write_b32 v40, v41
	v_add_u32_e32 v40, 4, v40
	s_or_b64 exec, exec, s[0:1]
	v_cmp_le_u32_e32 vcc, s22, v6
	s_and_saveexec_b64 s[0:1], vcc
	v_or_b32_e32 v41, 0x180, v11
	ds_write_b32 v40, v41
	v_add_u32_e32 v40, 4, v40
	s_or_b64 exec, exec, s[0:1]
	v_cmp_le_u32_e32 vcc, s22, v7
	s_and_saveexec_b64 s[0:1], vcc
	v_or_b32_e32 v41, 0x1c0, v11
	ds_write_b32 v40, v41
	v_add_u32_e32 v40, 4, v40
	s_or_b64 exec, exec, s[0:1]
	s_and_b64 vcc, exec, s[14:15]
	s_cbranch_vccnz .Lcmp_c1_g0
	v_cmp_le_u32_e32 vcc, s22, v18
	s_and_saveexec_b64 s[0:1], vcc
	v_or_b32_e32 v41, 0x200, v11
	ds_write_b32 v40, v41
	v_add_u32_e32 v40, 4, v40
	s_or_b64 exec, exec, s[0:1]
	v_cmp_le_u32_e32 vcc, s22, v16
	s_and_saveexec_b64 s[0:1], vcc
	v_or_b32_e32 v41, 0x240, v11
	ds_write_b32 v40, v41
	v_add_u32_e32 v40, 4, v40
	s_or_b64 exec, exec, s[0:1]
	v_cmp_le_u32_e32 vcc, s22, v21
	s_and_saveexec_b64 s[0:1], vcc
	v_or_b32_e32 v41, 0x280, v11
	ds_write_b32 v40, v41
	v_add_u32_e32 v40, 4, v40
	s_or_b64 exec, exec, s[0:1]
	v_cmp_le_u32_e32 vcc, s22, v17
	s_and_saveexec_b64 s[0:1], vcc
	v_or_b32_e32 v41, 0x2c0, v11
	ds_write_b32 v40, v41
	v_add_u32_e32 v40, 4, v40
	s_or_b64 exec, exec, s[0:1]
	v_cmp_le_u32_e32 vcc, s22, v22
	s_and_saveexec_b64 s[0:1], vcc
	v_or_b32_e32 v41, 0x300, v11
	ds_write_b32 v40, v41
	v_add_u32_e32 v40, 4, v40
	s_or_b64 exec, exec, s[0:1]
	v_cmp_le_u32_e32 vcc, s22, v19
	s_and_saveexec_b64 s[0:1], vcc
	v_or_b32_e32 v41, 0x340, v11
	ds_write_b32 v40, v41
	v_add_u32_e32 v40, 4, v40
	s_or_b64 exec, exec, s[0:1]
	v_cmp_le_u32_e32 vcc, s22, v23
	s_and_saveexec_b64 s[0:1], vcc
	v_or_b32_e32 v41, 0x380, v11
	ds_write_b32 v40, v41
	v_add_u32_e32 v40, 4, v40
	s_or_b64 exec, exec, s[0:1]
	v_cmp_le_u32_e32 vcc, s22, v20
	s_and_saveexec_b64 s[0:1], vcc
	v_or_b32_e32 v41, 0x3c0, v11
	ds_write_b32 v40, v41
	v_add_u32_e32 v40, 4, v40
	s_or_b64 exec, exec, s[0:1]
.Lcmp_c1_g0:
	s_and_b64 vcc, exec, s[12:13]
	s_cbranch_vccnz .Lcmp_c1_g1
	v_cmp_le_u32_e32 vcc, s22, v26
	s_and_saveexec_b64 s[0:1], vcc
	v_or_b32_e32 v41, 0x400, v11
	ds_write_b32 v40, v41
	v_add_u32_e32 v40, 4, v40
	s_or_b64 exec, exec, s[0:1]
	v_cmp_le_u32_e32 vcc, s22, v24
	s_and_saveexec_b64 s[0:1], vcc
	v_or_b32_e32 v41, 0x440, v11
	ds_write_b32 v40, v41
	v_add_u32_e32 v40, 4, v40
	s_or_b64 exec, exec, s[0:1]
	v_cmp_le_u32_e32 vcc, s22, v28
	s_and_saveexec_b64 s[0:1], vcc
	v_or_b32_e32 v41, 0x480, v11
	ds_write_b32 v40, v41
	v_add_u32_e32 v40, 4, v40
	s_or_b64 exec, exec, s[0:1]
	v_cmp_le_u32_e32 vcc, s22, v25
	s_and_saveexec_b64 s[0:1], vcc
	v_or_b32_e32 v41, 0x4c0, v11
	ds_write_b32 v40, v41
	v_add_u32_e32 v40, 4, v40
	s_or_b64 exec, exec, s[0:1]
	v_cmp_le_u32_e32 vcc, s22, v30
	s_and_saveexec_b64 s[0:1], vcc
	v_or_b32_e32 v41, 0x500, v11
	ds_write_b32 v40, v41
	v_add_u32_e32 v40, 4, v40
	s_or_b64 exec, exec, s[0:1]
	v_cmp_le_u32_e32 vcc, s22, v27
	s_and_saveexec_b64 s[0:1], vcc
	v_or_b32_e32 v41, 0x540, v11
	ds_write_b32 v40, v41
	v_add_u32_e32 v40, 4, v40
	s_or_b64 exec, exec, s[0:1]
	v_cmp_le_u32_e32 vcc, s22, v31
	s_and_saveexec_b64 s[0:1], vcc
	v_or_b32_e32 v41, 0x580, v11
	ds_write_b32 v40, v41
	v_add_u32_e32 v40, 4, v40
	s_or_b64 exec, exec, s[0:1]
	v_cmp_le_u32_e32 vcc, s22, v29
	s_and_saveexec_b64 s[0:1], vcc
	v_or_b32_e32 v41, 0x5c0, v11
	ds_write_b32 v40, v41
	v_add_u32_e32 v40, 4, v40
	s_or_b64 exec, exec, s[0:1]
.Lcmp_c1_g1:
	s_and_b64 vcc, exec, s[10:11]
	s_cbranch_vccnz .Lcmp_c1_g2
	v_cmp_le_u32_e32 vcc, s22, v34
	s_and_saveexec_b64 s[0:1], vcc
	v_or_b32_e32 v41, 0x600, v11
	ds_write_b32 v40, v41
	v_add_u32_e32 v40, 4, v40
	s_or_b64 exec, exec, s[0:1]
	v_cmp_le_u32_e32 vcc, s22, v32
	s_and_saveexec_b64 s[0:1], vcc
	v_or_b32_e32 v41, 0x640, v11
	ds_write_b32 v40, v41
	v_add_u32_e32 v40, 4, v40
	s_or_b64 exec, exec, s[0:1]
	v_cmp_le_u32_e32 vcc, s22, v36
	s_and_saveexec_b64 s[0:1], vcc
	v_or_b32_e32 v41, 0x680, v11
	ds_write_b32 v40, v41
	v_add_u32_e32 v40, 4, v40
	s_or_b64 exec, exec, s[0:1]
	v_cmp_le_u32_e32 vcc, s22, v33
	s_and_saveexec_b64 s[0:1], vcc
	v_or_b32_e32 v41, 0x6c0, v11
	ds_write_b32 v40, v41
	v_add_u32_e32 v40, 4, v40
	s_or_b64 exec, exec, s[0:1]
	v_cmp_le_u32_e32 vcc, s22, v38
	s_and_saveexec_b64 s[0:1], vcc
	v_or_b32_e32 v41, 0x700, v11
	ds_write_b32 v40, v41
	v_add_u32_e32 v40, 4, v40
	s_or_b64 exec, exec, s[0:1]
	v_cmp_le_u32_e32 vcc, s22, v35
	s_and_saveexec_b64 s[0:1], vcc
	v_or_b32_e32 v41, 0x740, v11
	ds_write_b32 v40, v41
	v_add_u32_e32 v40, 4, v40
	s_or_b64 exec, exec, s[0:1]
	v_cmp_le_u32_e32 vcc, s22, v39
	s_and_saveexec_b64 s[0:1], vcc
	v_or_b32_e32 v41, 0x780, v11
	ds_write_b32 v40, v41
	v_add_u32_e32 v40, 4, v40
	s_or_b64 exec, exec, s[0:1]
	v_cmp_le_u32_e32 vcc, s22, v37
	s_and_saveexec_b64 s[0:1], vcc
	v_or_b32_e32 v41, 0x7c0, v11
	ds_write_b32 v40, v41
	v_add_u32_e32 v40, 4, v40
	s_or_b64 exec, exec, s[0:1]
.Lcmp_c1_g2:
.LBB0_2554:
	s_mov_b64 s[0:1], 0
	s_mov_b64 s[66:67], s[6:7]
	s_mov_b64 s[64:65], s[4:5]

.LBB0_2880:
	v_readlane_b32 s64, v252, 7
	v_readlane_b32 s92, v252, 3
	s_and_b64 vcc, exec, s[42:43]
	v_readlane_b32 s96, v252, 18
	v_readlane_b32 s65, v252, 8
	v_readlane_b32 s66, v252, 9
	v_readlane_b32 s67, v252, 10
	v_readlane_b32 s88, v252, 20
	v_readlane_b32 s68, v251, 51
	v_readlane_b32 s93, v252, 4
	v_readlane_b32 s94, v252, 5
	v_readlane_b32 s95, v252, 6
	v_readlane_b32 s97, v252, 19
	v_readlane_b32 s89, v252, 21
	v_readlane_b32 s69, v251, 52
	v_readlane_b32 s70, v251, 53
	v_readlane_b32 s71, v251, 54
	v_readlane_b32 s72, v251, 55
	v_readlane_b32 s73, v251, 56
	v_readlane_b32 s74, v251, 57
	v_readlane_b32 s75, v251, 58
	v_readlane_b32 s76, v251, 59
	v_readlane_b32 s77, v251, 60
	v_readlane_b32 s78, v251, 61
	v_readlane_b32 s79, v251, 62
	v_readlane_b32 s80, v251, 63
	v_readlane_b32 s81, v252, 0
	v_readlane_b32 s82, v252, 1
	v_readlane_b32 s83, v252, 2
	s_cbranch_vccz .LBB0_2994
	v_add_u32_e32 v38, -1, v182
	v_cmp_lt_i32_e32 vcc, v38, v141
	v_add_u32_e32 v37, v84, v76
	v_add_u32_e32 v76, -2, v182
	v_cndmask_b32_e32 v38, v38, v182, vcc
	v_lshlrev_b32_e32 v38, 2, v38
	ds_bpermute_b32 v38, v38, v37
	v_cmp_ne_u32_e32 vcc, 0, v39
	s_waitcnt lgkmcnt(0)
	s_nop 0
	v_cndmask_b32_e32 v38, 0, v38, vcc
	v_cmp_lt_i32_e32 vcc, v76, v141
	v_add_u32_e32 v38, v38, v37
	s_nop 0
	v_cndmask_b32_e32 v76, v76, v182, vcc
	v_lshlrev_b32_e32 v76, 2, v76
	ds_bpermute_b32 v76, v76, v38
	v_cmp_lt_u32_e32 vcc, 1, v39
	s_waitcnt lgkmcnt(0)
	s_nop 0
	v_cndmask_b32_e32 v76, 0, v76, vcc
	v_add_u32_e32 v38, v76, v38
	v_add_u32_e32 v76, -4, v182
	v_cmp_lt_i32_e32 vcc, v76, v141
	s_nop 1
	v_cndmask_b32_e32 v76, v76, v182, vcc
	v_lshlrev_b32_e32 v76, 2, v76
	ds_bpermute_b32 v76, v76, v38
	v_cmp_lt_u32_e32 vcc, 3, v39
	s_waitcnt lgkmcnt(0)
	s_nop 0
	v_cndmask_b32_e32 v76, 0, v76, vcc
	v_add_u32_e32 v38, v76, v38
	v_add_u32_e32 v76, -8, v182
	v_cmp_lt_i32_e32 vcc, v76, v141
	s_nop 1
	v_cndmask_b32_e32 v76, v76, v182, vcc
	v_lshlrev_b32_e32 v76, 2, v76
	ds_bpermute_b32 v76, v76, v38
	v_cmp_lt_u32_e32 vcc, 7, v39
	s_waitcnt lgkmcnt(0)
	s_nop 0
	v_cndmask_b32_e32 v76, 0, v76, vcc
	v_add_u32_e32 v38, v76, v38
	v_add_u32_e32 v76, -16, v182
	v_cmp_lt_i32_e32 vcc, v76, v141
	s_nop 1
	v_cndmask_b32_e32 v76, v76, v182, vcc
	v_lshlrev_b32_e32 v76, 2, v76
	ds_bpermute_b32 v76, v76, v38
	v_cmp_lt_u32_e32 vcc, 15, v39
	s_waitcnt lgkmcnt(0)
	s_nop 0
	v_cndmask_b32_e32 v76, 0, v76, vcc
	v_add_u32_e32 v38, v76, v38
	v_subrev_u32_e32 v76, 32, v182
	v_cmp_lt_i32_e32 vcc, v76, v141
	v_sub_u32_e32 v37, v38, v37
	s_nop 0
	v_cndmask_b32_e32 v76, v76, v182, vcc
	v_lshlrev_b32_e32 v76, 2, v76
	ds_bpermute_b32 v76, v76, v38
	v_cmp_lt_u32_e32 vcc, 31, v39
	s_waitcnt lgkmcnt(0)
	s_nop 0
	v_cndmask_b32_e32 v76, 0, v76, vcc
	v_add_u32_e32 v37, v37, v76
	v_lshl_add_u32 v76, v37, 2, v138
	v_cmp_le_u32_e32 vcc, s18, v75
	s_and_saveexec_b64 s[0:1], vcc
	ds_write_b32 v76, v39
	v_add_u32_e32 v76, 4, v76
	s_or_b64 exec, exec, s[0:1]
	v_cmp_le_u32_e32 vcc, s18, v74
	s_and_saveexec_b64 s[0:1], vcc
	v_or_b32_e32 v38, 0x40, v39
	ds_write_b32 v76, v38
	v_add_u32_e32 v76, 4, v76
	s_or_b64 exec, exec, s[0:1]
	v_cmp_le_u32_e32 vcc, s18, v32
	s_and_saveexec_b64 s[0:1], vcc
	v_or_b32_e32 v38, 0x80, v39
	ds_write_b32 v76, v38
	v_add_u32_e32 v76, 4, v76
	s_or_b64 exec, exec, s[0:1]
	v_cmp_le_u32_e32 vcc, s18, v31
	s_and_saveexec_b64 s[0:1], vcc
	v_or_b32_e32 v38, 0xc0, v39
	ds_write_b32 v76, v38
	v_add_u32_e32 v76, 4, v76
	s_or_b64 exec, exec, s[0:1]
	v_cmp_le_u32_e32 vcc, s18, v30
	s_and_saveexec_b64 s[0:1], vcc
	v_or_b32_e32 v38, 0x100, v39
	ds_write_b32 v76, v38
	v_add_u32_e32 v76, 4, v76
	s_or_b64 exec, exec, s[0:1]
	v_cmp_le_u32_e32 vcc, s18, v29
	s_and_saveexec_b64 s[0:1], vcc
	v_or_b32_e32 v38, 0x140, v39
	ds_write_b32 v76, v38
	v_add_u32_e32 v76, 4, v76
	s_or_b64 exec, exec, s[0:1]
	v_cmp_le_u32_e32 vcc, s18, v28
	s_and_saveexec_b64 s[0:1], vcc
	v_or_b32_e32 v38, 0x180, v39
	ds_write_b32 v76, v38
	v_add_u32_e32 v76, 4, v76
	s_or_b64 exec, exec, s[0:1]
	v_cmp_le_u32_e32 vcc, s18, v27
	s_and_saveexec_b64 s[0:1], vcc
	v_or_b32_e32 v38, 0x1c0, v39
	ds_write_b32 v76, v38
	v_add_u32_e32 v76, 4, v76
	s_or_b64 exec, exec, s[0:1]
	v_cmp_le_u32_e32 vcc, s18, v24
	s_and_saveexec_b64 s[0:1], vcc
	v_or_b32_e32 v38, 0x200, v39
	ds_write_b32 v76, v38
	v_add_u32_e32 v76, 4, v76
	s_or_b64 exec, exec, s[0:1]
	v_cmp_le_u32_e32 vcc, s18, v23
	s_and_saveexec_b64 s[0:1], vcc
	v_or_b32_e32 v38, 0x240, v39
	ds_write_b32 v76, v38
	v_add_u32_e32 v76, 4, v76
	s_or_b64 exec, exec, s[0:1]
	v_cmp_le_u32_e32 vcc, s18, v26
	s_and_saveexec_b64 s[0:1], vcc
	v_or_b32_e32 v38, 0x280, v39
	ds_write_b32 v76, v38
	v_add_u32_e32 v76, 4, v76
	s_or_b64 exec, exec, s[0:1]
	v_cmp_le_u32_e32 vcc, s18, v25
	s_and_saveexec_b64 s[0:1], vcc
	v_or_b32_e32 v38, 0x2c0, v39
	ds_write_b32 v76, v38
	v_add_u32_e32 v76, 4, v76
	s_or_b64 exec, exec, s[0:1]
	v_cmp_le_u32_e32 vcc, s18, v22
	s_and_saveexec_b64 s[0:1], vcc
	v_or_b32_e32 v38, 0x300, v39
	ds_write_b32 v76, v38
	v_add_u32_e32 v76, 4, v76
	s_or_b64 exec, exec, s[0:1]
	v_cmp_le_u32_e32 vcc, s18, v21
	s_and_saveexec_b64 s[0:1], vcc
	v_or_b32_e32 v38, 0x340, v39
	ds_write_b32 v76, v38
	v_add_u32_e32 v76, 4, v76
	s_or_b64 exec, exec, s[0:1]
	v_cmp_le_u32_e32 vcc, s18, v20
	s_and_saveexec_b64 s[0:1], vcc
	v_or_b32_e32 v38, 0x380, v39
	ds_write_b32 v76, v38
	v_add_u32_e32 v76, 4, v76
	s_or_b64 exec, exec, s[0:1]
	v_cmp_le_u32_e32 vcc, s18, v19
	s_and_saveexec_b64 s[0:1], vcc
	v_or_b32_e32 v38, 0x3c0, v39
	ds_write_b32 v76, v38
	v_add_u32_e32 v76, 4, v76
	s_or_b64 exec, exec, s[0:1]
	v_cmp_le_u32_e32 vcc, s18, v16
	s_and_saveexec_b64 s[0:1], vcc
	v_or_b32_e32 v38, 0x400, v39
	ds_write_b32 v76, v38
	v_add_u32_e32 v76, 4, v76
	s_or_b64 exec, exec, s[0:1]
	v_cmp_le_u32_e32 vcc, s18, v18
	s_and_saveexec_b64 s[0:1], vcc
	v_or_b32_e32 v38, 0x440, v39
	ds_write_b32 v76, v38
	v_add_u32_e32 v76, 4, v76
	s_or_b64 exec, exec, s[0:1]
	v_cmp_le_u32_e32 vcc, s18, v1
	s_and_saveexec_b64 s[0:1], vcc
	v_or_b32_e32 v38, 0x480, v39
	ds_write_b32 v76, v38
	v_add_u32_e32 v76, 4, v76
	s_or_b64 exec, exec, s[0:1]
	v_cmp_le_u32_e32 vcc, s18, v2
	s_and_saveexec_b64 s[0:1], vcc
	v_or_b32_e32 v38, 0x4c0, v39
	ds_write_b32 v76, v38
	v_add_u32_e32 v76, 4, v76
	s_or_b64 exec, exec, s[0:1]
	v_cmp_le_u32_e32 vcc, s18, v3
	s_and_saveexec_b64 s[0:1], vcc
	v_or_b32_e32 v38, 0x500, v39
	ds_write_b32 v76, v38
	v_add_u32_e32 v76, 4, v76
	s_or_b64 exec, exec, s[0:1]
	v_cmp_le_u32_e32 vcc, s18, v4
	s_and_saveexec_b64 s[0:1], vcc
	v_or_b32_e32 v38, 0x540, v39
	ds_write_b32 v76, v38
	v_add_u32_e32 v76, 4, v76
	s_or_b64 exec, exec, s[0:1]
	v_cmp_le_u32_e32 vcc, s18, v5
	s_and_saveexec_b64 s[0:1], vcc
	v_or_b32_e32 v38, 0x580, v39
	ds_write_b32 v76, v38
	v_add_u32_e32 v76, 4, v76
	s_or_b64 exec, exec, s[0:1]
	v_cmp_le_u32_e32 vcc, s18, v6
	s_and_saveexec_b64 s[0:1], vcc
	v_or_b32_e32 v38, 0x5c0, v39
	ds_write_b32 v76, v38
	v_add_u32_e32 v76, 4, v76
	s_or_b64 exec, exec, s[0:1]
	v_cmp_le_u32_e32 vcc, s18, v7
	s_and_saveexec_b64 s[0:1], vcc
	v_or_b32_e32 v38, 0x600, v39
	ds_write_b32 v76, v38
	v_add_u32_e32 v76, 4, v76
	s_or_b64 exec, exec, s[0:1]
	v_cmp_le_u32_e32 vcc, s18, v8
	s_and_saveexec_b64 s[0:1], vcc
	v_or_b32_e32 v38, 0x640, v39
	ds_write_b32 v76, v38
	v_add_u32_e32 v76, 4, v76
	s_or_b64 exec, exec, s[0:1]
	v_cmp_le_u32_e32 vcc, s18, v9
	s_and_saveexec_b64 s[0:1], vcc
	v_or_b32_e32 v38, 0x680, v39
	ds_write_b32 v76, v38
	v_add_u32_e32 v76, 4, v76
	s_or_b64 exec, exec, s[0:1]
	v_cmp_le_u32_e32 vcc, s18, v10
	s_and_saveexec_b64 s[0:1], vcc
	v_or_b32_e32 v38, 0x6c0, v39
	ds_write_b32 v76, v38
	v_add_u32_e32 v76, 4, v76
	s_or_b64 exec, exec, s[0:1]
	v_cmp_le_u32_e32 vcc, s18, v11
	s_and_saveexec_b64 s[0:1], vcc
	v_or_b32_e32 v38, 0x700, v39
	ds_write_b32 v76, v38
	v_add_u32_e32 v76, 4, v76
	s_or_b64 exec, exec, s[0:1]
	v_cmp_le_u32_e32 vcc, s18, v12
	s_and_saveexec_b64 s[0:1], vcc
	v_or_b32_e32 v38, 0x740, v39
	ds_write_b32 v76, v38
	v_add_u32_e32 v76, 4, v76
	s_or_b64 exec, exec, s[0:1]
	v_cmp_le_u32_e32 vcc, s18, v13
	s_and_saveexec_b64 s[0:1], vcc
	v_or_b32_e32 v38, 0x780, v39
	ds_write_b32 v76, v38
	v_add_u32_e32 v76, 4, v76
	s_or_b64 exec, exec, s[0:1]
	v_cmp_le_u32_e32 vcc, s18, v14
	s_and_saveexec_b64 s[0:1], vcc
	v_or_b32_e32 v38, 0x7c0, v39
	ds_write_b32 v76, v38
	v_add_u32_e32 v76, 4, v76
	s_or_b64 exec, exec, s[0:1]
	v_cmp_le_u32_e32 vcc, s18, v15
	s_and_saveexec_b64 s[0:1], vcc
	v_or_b32_e32 v38, 0x800, v39
	ds_write_b32 v76, v38
	v_add_u32_e32 v76, 4, v76
	s_or_b64 exec, exec, s[0:1]
	v_cmp_le_u32_e32 vcc, s18, v34
	s_and_saveexec_b64 s[0:1], vcc
	v_or_b32_e32 v38, 0x840, v39
	ds_write_b32 v76, v38
	v_add_u32_e32 v76, 4, v76
	s_or_b64 exec, exec, s[0:1]
	v_cmp_le_u32_e32 vcc, s18, v33
	s_and_saveexec_b64 s[0:1], vcc
	v_or_b32_e32 v38, 0x880, v39
	ds_write_b32 v76, v38
	v_add_u32_e32 v76, 4, v76
	s_or_b64 exec, exec, s[0:1]
	v_cmp_le_u32_e32 vcc, s18, v36
	s_and_saveexec_b64 s[0:1], vcc
	v_or_b32_e32 v38, 0x8c0, v39
	ds_write_b32 v76, v38
	v_add_u32_e32 v76, 4, v76
	s_or_b64 exec, exec, s[0:1]
	v_cmp_le_u32_e32 vcc, s18, v35
	s_and_saveexec_b64 s[0:1], vcc
	v_or_b32_e32 v38, 0x900, v39
	ds_write_b32 v76, v38
	v_add_u32_e32 v76, 4, v76
	s_or_b64 exec, exec, s[0:1]
	v_cmp_le_u32_e32 vcc, s18, v17
	s_and_saveexec_b64 s[0:1], vcc
	v_or_b32_e32 v38, 0x940, v39
	ds_write_b32 v76, v38
	v_add_u32_e32 v76, 4, v76
	s_or_b64 exec, exec, s[0:1]
	v_cmp_le_u32_e32 vcc, s18, v50
	s_and_saveexec_b64 s[0:1], vcc
	v_or_b32_e32 v38, 0x980, v39
	ds_write_b32 v76, v38
	v_add_u32_e32 v76, 4, v76
	s_or_b64 exec, exec, s[0:1]
	v_cmp_le_u32_e32 vcc, s18, v47
	s_and_saveexec_b64 s[0:1], vcc
	v_or_b32_e32 v38, 0x9c0, v39
	ds_write_b32 v76, v38
	v_add_u32_e32 v76, 4, v76
	s_or_b64 exec, exec, s[0:1]
	s_and_b64 vcc, exec, s[14:15]
	s_cbranch_vccnz .Lcmp_c2_g0
	v_cmp_le_u32_e32 vcc, s18, v52
	s_and_saveexec_b64 s[0:1], vcc
	v_or_b32_e32 v38, 0xa00, v39
	ds_write_b32 v76, v38
	v_add_u32_e32 v76, 4, v76
	s_or_b64 exec, exec, s[0:1]
	v_cmp_le_u32_e32 vcc, s18, v49
	s_and_saveexec_b64 s[0:1], vcc
	v_or_b32_e32 v38, 0xa40, v39
	ds_write_b32 v76, v38
	v_add_u32_e32 v76, 4, v76
	s_or_b64 exec, exec, s[0:1]
	v_cmp_le_u32_e32 vcc, s18, v54
	s_and_saveexec_b64 s[0:1], vcc
	v_or_b32_e32 v38, 0xa80, v39
	ds_write_b32 v76, v38
	v_add_u32_e32 v76, 4, v76
	s_or_b64 exec, exec, s[0:1]
	v_cmp_le_u32_e32 vcc, s18, v51
	s_and_saveexec_b64 s[0:1], vcc
	v_or_b32_e32 v38, 0xac0, v39
	ds_write_b32 v76, v38
	v_add_u32_e32 v76, 4, v76
	s_or_b64 exec, exec, s[0:1]
	v_cmp_le_u32_e32 vcc, s18, v56
	s_and_saveexec_b64 s[0:1], vcc
	v_or_b32_e32 v38, 0xb00, v39
	ds_write_b32 v76, v38
	v_add_u32_e32 v76, 4, v76
	s_or_b64 exec, exec, s[0:1]
	v_cmp_le_u32_e32 vcc, s18, v53
	s_and_saveexec_b64 s[0:1], vcc
	v_or_b32_e32 v38, 0xb40, v39
	ds_write_b32 v76, v38
	v_add_u32_e32 v76, 4, v76
	s_or_b64 exec, exec, s[0:1]
	v_cmp_le_u32_e32 vcc, s18, v57
	s_and_saveexec_b64 s[0:1], vcc
	v_or_b32_e32 v38, 0xb80, v39
	ds_write_b32 v76, v38
	v_add_u32_e32 v76, 4, v76
	s_or_b64 exec, exec, s[0:1]
	v_cmp_le_u32_e32 vcc, s18, v55
	s_and_saveexec_b64 s[0:1], vcc
	v_or_b32_e32 v38, 0xbc0, v39
	ds_write_b32 v76, v38
	v_add_u32_e32 v76, 4, v76
	s_or_b64 exec, exec, s[0:1]
.Lcmp_c2_g0:
	s_and_b64 vcc, exec, s[12:13]
	s_cbranch_vccnz .Lcmp_c2_g1
	v_cmp_le_u32_e32 vcc, s18, v60
	s_and_saveexec_b64 s[0:1], vcc
	v_or_b32_e32 v38, 0xc00, v39
	ds_write_b32 v76, v38
	v_add_u32_e32 v76, 4, v76
	s_or_b64 exec, exec, s[0:1]
	v_cmp_le_u32_e32 vcc, s18, v58
	s_and_saveexec_b64 s[0:1], vcc
	v_or_b32_e32 v38, 0xc40, v39
	ds_write_b32 v76, v38
	v_add_u32_e32 v76, 4, v76
	s_or_b64 exec, exec, s[0:1]
	v_cmp_le_u32_e32 vcc, s18, v62
	s_and_saveexec_b64 s[0:1], vcc
	v_or_b32_e32 v38, 0xc80, v39
	ds_write_b32 v76, v38
	v_add_u32_e32 v76, 4, v76
	s_or_b64 exec, exec, s[0:1]
	v_cmp_le_u32_e32 vcc, s18, v59
	s_and_saveexec_b64 s[0:1], vcc
	v_or_b32_e32 v38, 0xcc0, v39
	ds_write_b32 v76, v38
	v_add_u32_e32 v76, 4, v76
	s_or_b64 exec, exec, s[0:1]
	v_cmp_le_u32_e32 vcc, s18, v64
	s_and_saveexec_b64 s[0:1], vcc
	v_or_b32_e32 v38, 0xd00, v39
	ds_write_b32 v76, v38
	v_add_u32_e32 v76, 4, v76
	s_or_b64 exec, exec, s[0:1]
	v_cmp_le_u32_e32 vcc, s18, v61
	s_and_saveexec_b64 s[0:1], vcc
	v_or_b32_e32 v38, 0xd40, v39
	ds_write_b32 v76, v38
	v_add_u32_e32 v76, 4, v76
	s_or_b64 exec, exec, s[0:1]
	v_cmp_le_u32_e32 vcc, s18, v65
	s_and_saveexec_b64 s[0:1], vcc
	v_or_b32_e32 v38, 0xd80, v39
	ds_write_b32 v76, v38
	v_add_u32_e32 v76, 4, v76
	s_or_b64 exec, exec, s[0:1]
	v_cmp_le_u32_e32 vcc, s18, v63
	s_and_saveexec_b64 s[0:1], vcc
	v_or_b32_e32 v38, 0xdc0, v39
	ds_write_b32 v76, v38
	v_add_u32_e32 v76, 4, v76
	s_or_b64 exec, exec, s[0:1]
.Lcmp_c2_g1:
	s_and_b64 vcc, exec, s[10:11]
	s_cbranch_vccnz .Lcmp_c2_g2
	v_cmp_le_u32_e32 vcc, s18, v68
	s_and_saveexec_b64 s[0:1], vcc
	v_or_b32_e32 v38, 0xe00, v39
	ds_write_b32 v76, v38
	v_add_u32_e32 v76, 4, v76
	s_or_b64 exec, exec, s[0:1]
	v_cmp_le_u32_e32 vcc, s18, v66
	s_and_saveexec_b64 s[0:1], vcc
	v_or_b32_e32 v38, 0xe40, v39
	ds_write_b32 v76, v38
	v_add_u32_e32 v76, 4, v76
	s_or_b64 exec, exec, s[0:1]
	v_cmp_le_u32_e32 vcc, s18, v70
	s_and_saveexec_b64 s[0:1], vcc
	v_or_b32_e32 v38, 0xe80, v39
	ds_write_b32 v76, v38
	v_add_u32_e32 v76, 4, v76
	s_or_b64 exec, exec, s[0:1]
	v_cmp_le_u32_e32 vcc, s18, v67
	s_and_saveexec_b64 s[0:1], vcc
	v_or_b32_e32 v38, 0xec0, v39
	ds_write_b32 v76, v38
	v_add_u32_e32 v76, 4, v76
	s_or_b64 exec, exec, s[0:1]
	v_cmp_le_u32_e32 vcc, s18, v72
	s_and_saveexec_b64 s[0:1], vcc
	v_or_b32_e32 v38, 0xf00, v39
	ds_write_b32 v76, v38
	v_add_u32_e32 v76, 4, v76
	s_or_b64 exec, exec, s[0:1]
	v_cmp_le_u32_e32 vcc, s18, v69
	s_and_saveexec_b64 s[0:1], vcc
	v_or_b32_e32 v38, 0xf40, v39
	ds_write_b32 v76, v38
	v_add_u32_e32 v76, 4, v76
	s_or_b64 exec, exec, s[0:1]
	v_cmp_le_u32_e32 vcc, s18, v73
	s_and_saveexec_b64 s[0:1], vcc
	v_or_b32_e32 v38, 0xf80, v39
	ds_write_b32 v76, v38
	v_add_u32_e32 v76, 4, v76
	s_or_b64 exec, exec, s[0:1]
	v_cmp_le_u32_e32 vcc, s18, v71
	s_and_saveexec_b64 s[0:1], vcc
	v_or_b32_e32 v38, 0xfc0, v39
	ds_write_b32 v76, v38
	v_add_u32_e32 v76, 4, v76
	s_or_b64 exec, exec, s[0:1]
.Lcmp_c2_g2:
.LBB0_2994:
	v_readlane_b32 s8, v251, 19
	v_readlane_b32 s0, v252, 26
	v_readlane_b32 s9, v251, 20
	v_readlane_b32 s10, v251, 21
	v_readlane_b32 s11, v251, 22
	v_readlane_b32 s12, v251, 23
	v_readlane_b32 s13, v251, 24
	v_readlane_b32 s14, v251, 25
	v_readlane_b32 s15, v251, 26
	v_readlane_b32 s16, v251, 27
	v_readlane_b32 s17, v251, 28
	s_lshl_b32 s6, s0, 10
	s_lshl_b32 s0, s0, 11
	v_readlane_b32 s18, v251, 29
	v_readlane_b32 s19, v251, 30
	v_readlane_b32 s20, v251, 31
	v_readlane_b32 s21, v251, 32
	v_readlane_b32 s22, v251, 33
	v_readlane_b32 s23, v251, 34
	s_mov_b64 s[8:9], s[16:17]
	s_add_u32 s0, s8, s0
	s_addc_u32 s1, s9, 0
	s_mov_b32 s7, 0
	s_mov_b64 s[2:3], -1
	s_mov_b64 s[10:11], s[18:19]
	s_mov_b64 s[12:13], s[20:21]
	s_mov_b64 s[14:15], s[22:23]
	v_readlane_b32 s70, v252, 26
	s_mov_b32 s72, s48
	s_movk_i32 s73, 0x100
	s_mov_b32 s74, 1
	s_branch .Lau_entry
.Lau_ret1:
	s_branch .LBB0_2341
.LBB0_3072:
	s_waitcnt vmcnt(0)
	v_readlane_b32 s66, v253, 16
	v_readlane_b32 s67, v253, 17
	s_barrier
	s_and_saveexec_b64 s[0:1], s[66:67]
	v_readlane_b32 s90, v253, 30
	v_readlane_b32 s84, v253, 48
	v_readlane_b32 s91, v253, 31
	s_cbranch_execz .LBB0_3124
	s_add_i32 s2, 0, 0x23ff0
	v_mov_b32_e32 v1, s2
	s_waitcnt vmcnt(0) expcnt(0) lgkmcnt(0)
	ds_read_b32 v3, v1
	s_add_i32 s2, 0, 0x23ff4
	v_mov_b32_e32 v1, s2
	ds_read_b32 v1, v1
	s_waitcnt lgkmcnt(1)
	v_cmp_ne_u32_e32 vcc, 0, v3
	s_cbranch_vccnz .LBB0_3088
	v_readlane_b32 s2, v253, 49
	v_readlane_b32 s8, v253, 0
	v_readlane_b32 s3, v253, 50
	v_readlane_b32 s10, v253, 2
	v_readlane_b32 s11, v253, 3
	v_readlane_b32 s18, v253, 10
	v_readlane_b32 s19, v253, 11
	s_load_dwordx2 s[6:7], s[2:3], 0x4
	s_mov_b64 s[10:11], s[18:19]
	s_add_u32 s2, s10, 0x1000
	s_addc_u32 s3, s11, 0
	s_add_u32 s4, s10, 0x1100
	v_readlane_b32 s16, v253, 8
	s_addc_u32 s5, s11, 0
	s_waitcnt lgkmcnt(0)
	s_mul_i32 s16, s6, s88
	s_add_u32 s6, s10, 0x1200
	s_mul_i32 s16, s16, s7
	s_addc_u32 s7, s11, 0
	v_readlane_b32 s9, v253, 1
	v_readlane_b32 s17, v253, 9
	s_add_u32 s8, s10, 0x1300
	s_addc_u32 s9, s11, 0
	s_mov_b32 s17, 1
	v_mov_b32_e32 v17, 0
	v_readlane_b32 s12, v253, 4
	v_readlane_b32 s13, v253, 5
	v_readlane_b32 s14, v253, 6
	v_readlane_b32 s15, v253, 7
	v_readlane_b32 s20, v253, 12
	v_readlane_b32 s21, v253, 13
	v_readlane_b32 s22, v253, 14
	v_readlane_b32 s23, v253, 15
	s_branch .LBB0_3076
